# v6 + NSA queue: next item index fetched at the start of the current item while index < 640 (atomic round trip hidden, no early reservation near the tail)
# baseline (speedup 1.0000x reference)
; __device__ __forceinline__ int tid_() { int t = threadIdx.x; asm volatile("" : "+v"(t)); return t; }
; #define LAS __attribute__((address_space(3)))
;     unsigned* ctr = (unsigned*)(a->ws + WS_CTL) + 64 * (l + 2 * rep);
;     for (;;) {
;         __syncthreads();
;         if (tid_() == 0) *(LAS int*)(lds + NSA_ITEM) = (int)atomicAdd(ctr, 1u);
;         __syncthreads();
;         const int it = *(LAS int*)(lds + NSA_ITEM);
;         if (it >= 1024) break;
;         nsa_item(a, lds, it);
;     }
; }
.LBB0_599:
	s_load_dwordx2 s[0:1], s[12:13], 0x120
	s_waitcnt lgkmcnt(0)
	s_add_u32 s2, s0, s10
	s_addc_u32 s3, s1, s11
	v_writelane_b32 v254, s2, 37
	s_nop 1
	v_writelane_b32 v254, s3, 38
	v_mov_b32_e32 v230, s2
	v_mov_b32_e32 v231, s3
	s_mov_b32 s99, 0
	s_add_u32 s2, s0, 0x8000000
	s_addc_u32 s3, s1, 0
	v_writelane_b32 v254, s2, 39
	s_nop 1
	v_writelane_b32 v254, s3, 40
	s_add_u32 s2, s0, 0x180000
	v_writelane_b32 v254, s2, 41
	s_addc_u32 s2, s1, 0
	v_writelane_b32 v254, s2, 42
	s_add_u32 s2, s0, 0x200000
	v_writelane_b32 v254, s2, 43
	v_writelane_b32 v254, s0, 44
	s_nop 1
	v_writelane_b32 v254, s1, 45
	s_addc_u32 s0, s1, 0
	v_writelane_b32 v254, s0, 46
	v_readfirstlane_b32 s100, v232
	s_nop 3
	s_lshr_b32 s100, s100, 6
	s_cmp_ge_u32 s100, 4
	s_cbranch_scc0 .Lnsa_prio_skip
	s_setprio 1

; __device__ __forceinline__ int tid_() { int t = threadIdx.x; asm volatile("" : "+v"(t)); return t; }
; #define LAS __attribute__((address_space(3)))
;     ...
;     for (;;) {
;         __syncthreads();
;         if (tid_() == 0) *(LAS int*)(lds + NSA_ITEM) = (int)atomicAdd(ctr, 1u);
;         __syncthreads();
;         const int it = *(LAS int*)(lds + NSA_ITEM);
.LBB0_603:
	v_mov_b32_e32 v0, v232
	s_barrier
	s_nop 0
	v_cmp_eq_u32_e32 vcc, 0, v0
	s_and_saveexec_b64 s[0:1], vcc
	s_cbranch_execz .LBB0_607
	s_mov_b64 s[4:5], exec
	v_mbcnt_lo_u32_b32 v0, s4, 0
	v_mbcnt_hi_u32_b32 v0, s5, v0
	v_cmp_eq_u32_e32 vcc, 0, v0
	s_and_saveexec_b64 s[2:3], vcc
	s_cbranch_execz .LBB0_606
	s_bcnt1_i32_b64 s4, s[4:5]
	v_mov_b32_e32 v1, s4
	v_readlane_b32 s4, v254, 37
	v_readlane_b32 s5, v254, 38
	s_nop 4
	s_cmp_eq_u32 s99, 0
	s_cbranch_scc0 .Lnsa_pf_use
	global_atomic_add v1, v193, v1, s[4:5] sc0
	s_branch .LBB0_606
.Lnsa_pf_use:
	s_waitcnt vmcnt(0)
	v_mov_b32_e32 v1, v191

; __device__ __forceinline__ int tid_() { int t = threadIdx.x; asm volatile("" : "+v"(t)); return t; }
; #define LAS __attribute__((address_space(3)))
; DI float sigmoidf_(float x) { return __builtin_amdgcn_rcpf(1.f + __expf(-x)); }
; DI float ldbf(const bf16* p) { return bf2f(*p); }
; DI void nsa_item(KA a, LAS unsigned char* lds, const int it) {
;     const int tid = tid_(), lane = tid & 63, w = tid >> 6, r = lane & 31, hf = lane >> 5;
;     const int qb = 31 - (it >> 5), bg = it & 31, b = bg >> 1, g = bg & 1, hh = w >> 1, head = g * 4 + hh, tql = 32 * (w & 1) + r;
;     unsigned char* ws = a->ws; const bf16* H = (const bf16*)(ws + WS_H); bf16* act = (bf16*)(ws + WS_ACT);
;     const size_t tokrow = (size_t)b * SEQ + 64 * qb + tql;
;     LAS bf16* Kt = (LAS bf16*)(lds + NSA_KT); LAS bf16* VT = (LAS bf16*)(lds + NSA_VT); LAS float* IMP = (LAS float*)(lds + NSA_IMP); LAS float* IMPT = (LAS float*)(lds + NSA_IMPT);
;     LAS unsigned* SELM = (LAS unsigned*)(lds + NSA_SELM); LAS int* LIST = (LAS int*)(lds + NSA_LIST); LAS int* NLIST = (LAS int*)(lds + NSA_NLIST);
;     bf16x8 bq[4];
; #pragma unroll
;     for (int s = 0; s < 4; ++s) bq[s] = *(const bf16x8*)(H + tokrow * HP + C_NQ + head * 64 + 16 * s + 8 * hf);
;     const float g0 = sigmoidf_(ldbf(H + tokrow * HP + C_NG + head * 3 + 0)), g1 = sigmoidf_(ldbf(H + tokrow * HP + C_NG + head * 3 + 1)), g2 = sigmoidf_(ldbf(H + tokrow * HP + C_NG + head * 3 + 2));
;     v4u kreg; v2u vr0, vr1;
;     const int skey = tid >> 3, sch = tid & 7, sdg = tid & 15, skp = tid >> 4;
;     ...
;     NSA_LOAD(0);
;     { const bf16* kc = (const bf16*)(ws + WS_KCMP) + (size_t)bg * 128 * 64; const bf16* vc = (const bf16*)(ws + WS_VCMP) + (size_t)bg * 128 * 64;
; #pragma unroll
;       for (int i = 0; i < 2; ++i) { const int idx = tid + NTHR * i; const int c = idx >> 3, ch = idx & 7; *(LAS v4u*)(Kt + c * PA + 8 * ch) = *(const v4u*)(kc + c * 64 + 8 * ch);
;           const int dg = idx & 15, kp = idx >> 4; const v2u v0 = *(const v2u*)(vc + (2 * kp) * 64 + 4 * dg), v1 = *(const v2u*)(vc + (2 * kp + 1) * 64 + 4 * dg);
;           LAS unsigned* d0 = (LAS unsigned*)(VT + (4 * dg) * PV + vpos(2 * kp));
;           d0[0] = (v0.x & 0xffffu) | (v1.x << 16); d0[PV / 2] = (v0.x >> 16) | (v1.x & 0xffff0000u); d0[PV] = (v0.y & 0xffffu) | (v1.y << 16); d0[3 * PV / 2] = (v0.y >> 16) | (v1.y & 0xffff0000u); } }
;     __syncthreads();
.LBB0_607:
	s_or_b64 exec, exec, s[0:1]
	v_readlane_b32 s0, v254, 6
	s_waitcnt lgkmcnt(0)
	s_barrier
	v_mov_b32_e32 v0, s0
	ds_read_b32 v0, v0
	s_movk_i32 s0, 0x3ff
	s_waitcnt lgkmcnt(0)
	v_cmp_lt_i32_e32 vcc, s0, v0
	v_readfirstlane_b32 s2, v0
	s_mov_b64 s[0:1], -1
	s_cbranch_vccnz .LBB0_602
	s_mov_b32 s99, 0
	s_cmpk_lt_u32 s2, 0x280
	s_cbranch_scc0 .Lnsa_pf_skip
	v_cmp_eq_u32_e32 vcc, 0, v232
	s_and_saveexec_b64 s[100:101], vcc
	global_atomic_add v191, v[230:231], v233, off sc0
	s_mov_b32 s99, 1
	s_mov_b64 exec, s[100:101]
.Lnsa_pf_skip:
	s_ashr_i32 s40, s2, 5
	s_sub_i32 s3, 31, s40
	s_lshl_b32 s0, s2, 10
	v_writelane_b32 v254, s3, 47
	v_mov_b32_e32 v87, v232
	s_and_b32 s1, s2, 31
	s_and_b32 s41, s2, 1
	s_and_b32 s6, s0, 0x7800
	s_lshl_b32 s0, s3, 6
	v_readlane_b32 s2, v254, 39
	v_readlane_b32 s3, v254, 40
	v_ashrrev_i32_e32 v132, 3, v87
	v_add_u32_e32 v0, s6, v132
	s_waitcnt vmcnt(5)
	v_mov_b64_e32 v[8:9], s[2:3]
	s_movk_i32 s5, 0x1c00
	s_lshl_b32 s90, s41, 7
	v_mad_i64_i32 v[0:1], s[2:3], v0, s5, v[8:9]
	v_and_b32_e32 v133, -2, v132
	s_waitcnt vmcnt(4)
	v_lshl_add_u64 v[10:11], v[0:1], 0, s[90:91]
	v_add_u32_e32 v0, s6, v133
	v_writelane_b32 v254, s6, 48
	v_mad_i64_i32 v[0:1], s[2:3], v0, s5, v[8:9]
	s_or_b32 s90, s90, 0x1760
	s_add_i32 s4, s6, s0
	v_lshl_add_u64 v[4:5], v[0:1], 0, s[90:91]
	v_lshlrev_b32_e32 v0, 2, v87
	s_lshl_b32 s1, s1, 14
	v_readlane_b32 s2, v254, 41
	v_and_b32_e32 v136, 60, v0
	s_add_u32 s2, s2, s1
	v_readlane_b32 s3, v254, 42
	v_lshlrev_b32_e32 v0, 4, v87
	s_addc_u32 s3, s3, 0
	s_waitcnt vmcnt(3)
	v_and_b32_e32 v12, 0x70, v0
	v_mov_b32_e32 v13, v193
	s_waitcnt vmcnt(2)
	v_lshlrev_b32_e32 v14, 6, v132
	v_lshl_add_u64 v[6:7], s[2:3], 0, v[12:13]
	v_ashrrev_i32_e32 v15, 31, v14
	v_lshl_add_u64 v[0:1], v[14:15], 1, v[6:7]
	v_readlane_b32 s2, v254, 43
	v_lshlrev_b32_e32 v88, 1, v136
	v_mov_b32_e32 v89, v193
	global_load_dwordx4 v[0:3], v[0:1], off
	s_add_u32 s2, s2, s1
	v_readlane_b32 s1, v254, 46
	s_addc_u32 s3, s1, 0
	v_and_b32_e32 v18, 0xffffff80, v14
	v_or_b32_e32 v14, 64, v14
	v_lshl_add_u64 v[20:21], v[4:5], 0, v[88:89]
	s_movk_i32 s1, 0x1000
	v_lshl_add_u64 v[16:17], s[2:3], 0, v[88:89]
	v_ashrrev_i32_e32 v19, 31, v18
	v_ashrrev_i32_e32 v15, 31, v14
	v_add_co_u32_e32 v4, vcc, s1, v20
	v_lshl_add_u64 v[18:19], v[18:19], 1, v[16:17]
	v_lshl_add_u64 v[14:15], v[14:15], 1, v[16:17]
	v_addc_co_u32_e32 v5, vcc, 0, v21, vcc
	global_load_dwordx2 v[18:19], v[18:19], off
	s_nop 0
	global_load_dwordx2 v[14:15], v[14:15], off
	v_ashrrev_i32_e32 v143, 6, v87
	global_load_dwordx2 v[94:95], v[4:5], off offset:3072
	v_add_u32_e32 v4, 0x200, v87
	v_ashrrev_i32_e32 v13, 3, v4
	v_lshlrev_b32_e32 v22, 6, v13
	v_ashrrev_i32_e32 v23, 31, v22
	v_lshl_add_u64 v[4:5], v[22:23], 1, v[6:7]
	global_load_dwordx4 v[4:7], v[4:5], off
	v_and_b32_e32 v24, 0xffffff80, v22
	v_ashrrev_i32_e32 v25, 31, v24
	v_or_b32_e32 v22, 64, v22
	v_lshl_add_u64 v[24:25], v[24:25], 1, v[16:17]
	v_ashrrev_i32_e32 v23, 31, v22
	global_load_dwordx2 v[24:25], v[24:25], off
	v_lshl_add_u64 v[16:17], v[22:23], 1, v[16:17]
	global_load_dwordx2 v[16:17], v[16:17], off
	v_and_b32_e32 v89, 31, v87
	v_ashrrev_i32_e32 v146, 7, v87
	v_lshlrev_b32_e32 v22, 5, v143
	v_lshl_add_u32 v28, s41, 2, v146
	v_and_or_b32 v135, v22, 32, v89
	v_or_b32_e32 v86, s4, v135
	v_lshlrev_b32_e32 v84, 6, v28
	v_bfe_u32 v137, v87, 5, 1
	v_mad_u64_u32 v[8:9], s[2:3], v86, s5, v[8:9]
	v_ashrrev_i32_e32 v85, 31, v84
	v_lshl_add_u64 v[22:23], v[84:85], 1, v[8:9]
	v_lshlrev_b32_e32 v90, 4, v137
	v_mov_b32_e32 v91, v193
	v_lshl_add_u64 v[22:23], v[22:23], 0, v[90:91]
	s_mov_b64 s[2:3], 0x1060
	v_lshl_add_u64 v[26:27], v[22:23], 0, s[2:3]
	v_add_co_u32_e32 v22, vcc, s1, v22
	s_mov_b64 s[2:3], 0x1a60
	s_nop 0
	v_addc_co_u32_e32 v23, vcc, 0, v23, vcc
	global_load_dwordx4 v[64:67], v[26:27], off offset:32
	global_load_dwordx4 v[68:71], v[26:27], off offset:64
	global_load_dwordx4 v[72:75], v[22:23], off offset:96
	global_load_dwordx4 v[76:79], v[26:27], off offset:96
	v_lshl_add_u32 v22, v28, 1, v28
	v_ashrrev_i32_e32 v23, 31, v22
	v_lshl_add_u64 v[8:9], v[22:23], 1, v[8:9]
	v_and_b32_e32 v141, 7, v87
	v_lshl_add_u64 v[22:23], v[8:9], 0, s[2:3]
	v_add_co_u32_e32 v8, vcc, s1, v8
	v_lshlrev_b32_e32 v192, 4, v141
	s_nop 0
	v_addc_co_u32_e32 v9, vcc, 0, v9, vcc
	v_lshl_add_u64 v[10:11], v[10:11], 0, v[192:193]
	v_add_co_u32_e32 v10, vcc, s1, v10
	s_movk_i32 s4, 0x110
	s_nop 0
	v_addc_co_u32_e32 v11, vcc, 0, v11, vcc
	global_load_dword v142, v[8:9], off offset:2656
	global_load_dwordx4 v[80:83], v[10:11], off offset:1632
	global_load_dwordx2 v[96:97], v[20:21], off
	global_load_ushort v91, v[22:23], off offset:4
	v_add_u32_e32 v8, 0, v12
	v_mad_u32_u24 v9, v136, s4, 0
	v_mad_u64_u32 v[10:11], s[2:3], v132, s75, v[8:9]
	v_and_b32_e32 v140, -14, v132
	s_mov_b32 s1, 0xffff0000
	s_waitcnt vmcnt(14)
	ds_write_b128 v10, v[0:3]
	v_lshrrev_b32_e32 v0, 1, v132
	v_and_b32_e32 v138, 4, v0
	v_lshlrev_b32_e32 v0, 1, v132
	v_and_b32_e32 v139, 8, v0
	v_lshl_add_u32 v0, v140, 1, v9
	v_lshlrev_b32_e32 v1, 1, v138
	v_lshlrev_b32_e32 v2, 1, v139
	v_add3_u32 v0, v0, v1, v2
	v_add_u32_e32 v0, 0x4800, v0
	v_add_u32_e32 v112, 0, v90
	v_mad_u32_u24 v92, v89, s75, v112
	v_lshlrev_b32_e32 v93, 6, v137
	s_cmp_gt_i32 s40, 15
	s_waitcnt vmcnt(13)
	v_and_b32_e32 v1, 0xffff, v18
	v_lshrrev_b32_e32 v2, 16, v18
	s_waitcnt vmcnt(12)
	v_lshl_or_b32 v1, v14, 16, v1
	v_and_or_b32 v2, v14, s1, v2
	ds_write2_b32 v0, v1, v2 offset1:68
	v_and_b32_e32 v1, 0xffff, v19
	v_lshrrev_b32_e32 v2, 16, v19
	v_lshl_or_b32 v1, v15, 16, v1
	v_and_or_b32 v2, v15, s1, v2
	ds_write2_b32 v0, v1, v2 offset0:136 offset1:204
	v_mad_u64_u32 v[0:1], s[2:3], v13, s75, v[8:9]
	s_waitcnt vmcnt(10)
	ds_write_b128 v0, v[4:7]
	v_lshlrev_b32_e32 v0, 1, v13
	v_and_b32_e32 v0, 0xffffffe4, v0
	v_lshlrev_b32_e32 v2, 2, v13
	v_add_u32_e32 v0, v9, v0
	v_and_b32_e32 v1, 8, v13
	v_and_b32_e32 v2, 16, v2
	v_add3_u32 v0, v0, v1, v2
	s_waitcnt vmcnt(9)
	v_and_b32_e32 v1, 0xffff, v24
	v_lshrrev_b32_e32 v2, 16, v24
	s_waitcnt vmcnt(8)
	v_lshl_or_b32 v1, v16, 16, v1
	v_and_or_b32 v2, v16, s1, v2
	v_add_u32_e32 v0, 0x4800, v0
	ds_write2_b32 v0, v1, v2 offset1:68
	v_and_b32_e32 v1, 0xffff, v25
	v_lshrrev_b32_e32 v2, 16, v25
	v_lshl_or_b32 v1, v17, 16, v1
	v_and_or_b32 v2, v17, s1, v2
	ds_write2_b32 v0, v1, v2 offset0:136 offset1:204
	s_waitcnt lgkmcnt(0)
	s_barrier
; #define LAS __attribute__((address_space(3)))
; DI f32x16 mma32(bf16x8 a, bf16x8 b, f32x16 c) { return __builtin_amdgcn_mfma_f32_32x32x16_bf16(a, b, c, 0, 0, 0); }
; DI int crow(int i, int hf) { return (i & 3) + 8 * (i >> 2) + 4 * hf; }
; DI void nsa_item(KA a, LAS unsigned char* lds, const int it) {
;     ...
;         f32x16 st[4] = {ZERO16, ZERO16, ZERO16, ZERO16};
; #pragma unroll
;         for (int k4 = 0; k4 < 4; ++k4)
; #pragma unroll
;             for (int s = 0; s < 4; ++s) { const bf16x8 af = *(const LAS bf16x8*)(Kt + (32 * k4 + r) * PA + 16 * s + 8 * hf); st[k4] = mma32(af, bq[s], st[k4]); }
;         const int tq = 64 * qb + tql; float mx = -INFINITY;
; #pragma unroll
;         for (int k4 = 0; k4 < 4; ++k4)
; #pragma unroll
;             for (int i = 0; i < 16; ++i) { const int c = 32 * k4 + crow(i, hf); const bool ok = (16 * c + 31 <= tq); st[k4][i] = ok ? st[k4][i] : -INFINITY; mx = fmaxf(mx, st[k4][i]); }
	ds_read_b128 v[0:3], v92
	ds_read_b128 v[98:101], v92 offset:13856
	s_waitcnt vmcnt(5) lgkmcnt(1)
	v_mfma_f32_32x32x16_bf16 v[48:63], v[0:3], v[72:75], 0
	ds_read_b128 v[0:3], v92 offset:32
	s_waitcnt lgkmcnt(0)
	v_mfma_f32_32x32x16_bf16 v[48:63], v[0:3], v[64:67], v[48:63]
	ds_read_b128 v[0:3], v92 offset:64
	s_waitcnt lgkmcnt(0)
	v_mfma_f32_32x32x16_bf16 v[48:63], v[0:3], v[68:71], v[48:63]
	ds_read_b128 v[0:3], v92 offset:96
	s_waitcnt vmcnt(4) lgkmcnt(0)
	v_mfma_f32_32x32x16_bf16 v[48:63], v[0:3], v[76:79], v[48:63]
	ds_read_b128 v[0:3], v92 offset:4608
	s_waitcnt lgkmcnt(0)
	v_mfma_f32_32x32x16_bf16 v[32:47], v[0:3], v[72:75], 0
	ds_read_b128 v[0:3], v92 offset:4640
	s_waitcnt lgkmcnt(0)
	v_mfma_f32_32x32x16_bf16 v[32:47], v[0:3], v[64:67], v[32:47]
	ds_read_b128 v[0:3], v92 offset:4672
	s_waitcnt lgkmcnt(0)
	v_mfma_f32_32x32x16_bf16 v[32:47], v[0:3], v[68:71], v[32:47]
	ds_read_b128 v[0:3], v92 offset:4704
	s_waitcnt lgkmcnt(0)
	v_mfma_f32_32x32x16_bf16 v[32:47], v[0:3], v[76:79], v[32:47]
	ds_read_b128 v[0:3], v92 offset:9216
	s_waitcnt lgkmcnt(0)
	v_mfma_f32_32x32x16_bf16 v[16:31], v[0:3], v[72:75], 0
	ds_read_b128 v[0:3], v92 offset:9248
	s_waitcnt lgkmcnt(0)
	v_mfma_f32_32x32x16_bf16 v[16:31], v[0:3], v[64:67], v[16:31]
	ds_read_b128 v[0:3], v92 offset:9280
	s_waitcnt lgkmcnt(0)
	v_mfma_f32_32x32x16_bf16 v[16:31], v[0:3], v[68:71], v[16:31]
	ds_read_b128 v[0:3], v92 offset:9312
	s_waitcnt lgkmcnt(0)
	v_mfma_f32_32x32x16_bf16 v[16:31], v[0:3], v[76:79], v[16:31]
	ds_read_b128 v[0:3], v92 offset:13824
	s_waitcnt lgkmcnt(0)
	v_mfma_f32_32x32x16_bf16 v[0:15], v[0:3], v[72:75], 0
	v_mfma_f32_32x32x16_bf16 v[0:15], v[98:101], v[64:67], v[0:15]
	ds_read_b128 v[98:101], v92 offset:13888
	s_waitcnt lgkmcnt(0)
	v_mfma_f32_32x32x16_bf16 v[0:15], v[98:101], v[68:71], v[0:15]
	ds_read_b128 v[98:101], v92 offset:13920
	v_or_b32_e32 v92, s0, v135
	s_mov_b32 s0, 0xff800000
	s_waitcnt lgkmcnt(0)
	v_mfma_f32_32x32x16_bf16 v[0:15], v[98:101], v[76:79], v[0:15]
	v_or_b32_e32 v98, 31, v93
	v_cmp_le_u32_e32 vcc, v98, v92
	v_or_b32_e32 v98, 47, v93
	v_or_b32_e32 v99, 63, v93
	v_cndmask_b32_e32 v48, v240, v48, vcc
	v_cmp_le_u32_e32 vcc, v98, v92
	s_nop 1
	v_cndmask_b32_e32 v49, v240, v49, vcc
	v_cmp_le_u32_e32 vcc, v99, v92
	v_add_u32_e32 v99, 0x4f, v93
	v_max3_f32 v98, v48, s0, v49
	v_cndmask_b32_e32 v50, v240, v50, vcc
	v_cmp_le_u32_e32 vcc, v99, v92
	v_or_b32_e32 v99, 0x9f, v93
	s_nop 0
	v_cndmask_b32_e32 v51, v240, v51, vcc
	v_cmp_le_u32_e32 vcc, v99, v92
	v_or_b32_e32 v99, 0xaf, v93
	v_max3_f32 v98, v98, v50, v51
	v_cndmask_b32_e32 v52, v240, v52, vcc
	v_cmp_le_u32_e32 vcc, v99, v92
	v_or_b32_e32 v99, 0xbf, v93
	s_nop 0
	v_cndmask_b32_e32 v53, v240, v53, vcc
	v_cmp_le_u32_e32 vcc, v99, v92
	v_add_u32_e32 v99, 0xcf, v93
	v_max3_f32 v98, v98, v52, v53
	v_cndmask_b32_e32 v54, v240, v54, vcc
	v_cmp_le_u32_e32 vcc, v99, v92
	v_or_b32_e32 v99, 0x11f, v93
	s_nop 0
	v_cndmask_b32_e32 v55, v240, v55, vcc
	v_cmp_le_u32_e32 vcc, v99, v92
	v_or_b32_e32 v99, 0x12f, v93
	v_max3_f32 v98, v98, v54, v55
	v_cndmask_b32_e32 v56, v240, v56, vcc
	v_cmp_le_u32_e32 vcc, v99, v92
	v_or_b32_e32 v99, 0x13f, v93
	s_nop 0
	v_cndmask_b32_e32 v57, v240, v57, vcc
	v_cmp_le_u32_e32 vcc, v99, v92
	v_add_u32_e32 v99, 0x14f, v93
	v_max3_f32 v98, v98, v56, v57
	v_cndmask_b32_e32 v58, v240, v58, vcc
	v_cmp_le_u32_e32 vcc, v99, v92
	v_or_b32_e32 v99, 0x19f, v93
	s_nop 0
	v_cndmask_b32_e32 v59, v240, v59, vcc
	v_cmp_le_u32_e32 vcc, v99, v92
	v_or_b32_e32 v99, 0x1af, v93
	v_max3_f32 v98, v98, v58, v59
	v_cndmask_b32_e32 v60, v240, v60, vcc
	v_cmp_le_u32_e32 vcc, v99, v92
	v_or_b32_e32 v99, 0x1bf, v93
	s_nop 0
	v_cndmask_b32_e32 v61, v240, v61, vcc
	v_cmp_le_u32_e32 vcc, v99, v92
	v_add_u32_e32 v99, 0x1cf, v93
	v_max3_f32 v98, v98, v60, v61
	v_cndmask_b32_e32 v62, v240, v62, vcc
	v_cmp_le_u32_e32 vcc, v99, v92
	v_or_b32_e32 v99, 0x21f, v93
	s_nop 0
	v_cndmask_b32_e32 v63, v240, v63, vcc
	v_cmp_le_u32_e32 vcc, v99, v92
	v_or_b32_e32 v99, 0x22f, v93
	v_max3_f32 v98, v98, v62, v63
	v_cndmask_b32_e32 v32, v240, v32, vcc
	v_cmp_le_u32_e32 vcc, v99, v92
	v_or_b32_e32 v99, 0x23f, v93
	s_nop 0
	v_cndmask_b32_e32 v33, v240, v33, vcc
	v_cmp_le_u32_e32 vcc, v99, v92
	v_add_u32_e32 v99, 0x24f, v93
	v_max3_f32 v98, v98, v32, v33
	v_cndmask_b32_e32 v34, v240, v34, vcc
	v_cmp_le_u32_e32 vcc, v99, v92
	v_or_b32_e32 v99, 0x29f, v93
	s_nop 0
	v_cndmask_b32_e32 v35, v240, v35, vcc
	v_cmp_le_u32_e32 vcc, v99, v92
	v_or_b32_e32 v99, 0x2af, v93
	v_max3_f32 v98, v98, v34, v35
	v_cndmask_b32_e32 v36, v240, v36, vcc
	v_cmp_le_u32_e32 vcc, v99, v92
	v_or_b32_e32 v99, 0x2bf, v93
	s_nop 0
	v_cndmask_b32_e32 v37, v240, v37, vcc
	v_cmp_le_u32_e32 vcc, v99, v92
	v_add_u32_e32 v99, 0x2cf, v93
	v_max3_f32 v98, v98, v36, v37
	v_cndmask_b32_e32 v38, v240, v38, vcc
	v_cmp_le_u32_e32 vcc, v99, v92
	v_or_b32_e32 v99, 0x31f, v93
	s_nop 0
	v_cndmask_b32_e32 v39, v240, v39, vcc
	v_cmp_le_u32_e32 vcc, v99, v92
	v_or_b32_e32 v99, 0x32f, v93
	v_max3_f32 v98, v98, v38, v39
	v_cndmask_b32_e32 v40, v240, v40, vcc
	v_cmp_le_u32_e32 vcc, v99, v92
	v_or_b32_e32 v99, 0x33f, v93
	s_nop 0
	v_cndmask_b32_e32 v41, v240, v41, vcc
	v_cmp_le_u32_e32 vcc, v99, v92
	v_add_u32_e32 v99, 0x34f, v93
	v_max3_f32 v98, v98, v40, v41
	v_cndmask_b32_e32 v42, v240, v42, vcc
	v_cmp_le_u32_e32 vcc, v99, v92
	v_or_b32_e32 v99, 0x39f, v93
	s_nop 0
	v_cndmask_b32_e32 v43, v240, v43, vcc
	v_cmp_le_u32_e32 vcc, v99, v92
	v_or_b32_e32 v99, 0x3af, v93
	v_max3_f32 v98, v98, v42, v43
	v_cndmask_b32_e32 v44, v240, v44, vcc
	v_cmp_le_u32_e32 vcc, v99, v92
	v_or_b32_e32 v99, 0x3bf, v93
	s_nop 0
	v_cndmask_b32_e32 v45, v240, v45, vcc
	v_cmp_le_u32_e32 vcc, v99, v92
; DI int crow(int i, int hf) { return (i & 3) + 8 * (i >> 2) + 4 * hf; }
; DI void nsa_item(KA a, LAS unsigned char* lds, const int it) {
;     ...
;         const int tq = 64 * qb + tql; float mx = -INFINITY;
; #pragma unroll
;         for (int k4 = 0; k4 < 4; ++k4)
; #pragma unroll
;             for (int i = 0; i < 16; ++i) { const int c = 32 * k4 + crow(i, hf); const bool ok = (16 * c + 31 <= tq); st[k4][i] = ok ? st[k4][i] : -INFINITY; mx = fmaxf(mx, st[k4][i]); }
;         mx = fmaxf(mx, __shfl_xor(mx, 32)); const float mref = (mx == -INFINITY) ? 0.f : mx; float ls = 0.f;
	v_add_u32_e32 v99, 0x3cf, v93
	v_max3_f32 v98, v98, v44, v45
	v_cndmask_b32_e32 v46, v240, v46, vcc
	v_cmp_le_u32_e32 vcc, v99, v92
	v_or_b32_e32 v99, 0x41f, v93
	s_nop 0
	v_cndmask_b32_e32 v47, v240, v47, vcc
	v_cmp_le_u32_e32 vcc, v99, v92
	v_or_b32_e32 v99, 0x42f, v93
	v_max3_f32 v98, v98, v46, v47
	v_cndmask_b32_e32 v16, v240, v16, vcc
	v_cmp_le_u32_e32 vcc, v99, v92
	v_or_b32_e32 v99, 0x43f, v93
	s_nop 0
	v_cndmask_b32_e32 v17, v240, v17, vcc
	v_cmp_le_u32_e32 vcc, v99, v92
	v_add_u32_e32 v99, 0x44f, v93
	v_max3_f32 v98, v98, v16, v17
	v_cndmask_b32_e32 v18, v240, v18, vcc
	v_cmp_le_u32_e32 vcc, v99, v92
	v_or_b32_e32 v99, 0x49f, v93
	s_nop 0
	v_cndmask_b32_e32 v19, v240, v19, vcc
	v_cmp_le_u32_e32 vcc, v99, v92
	v_or_b32_e32 v99, 0x4af, v93
	v_max3_f32 v98, v98, v18, v19
	v_cndmask_b32_e32 v20, v240, v20, vcc
	v_cmp_le_u32_e32 vcc, v99, v92
	v_or_b32_e32 v99, 0x4bf, v93
	s_nop 0
	v_cndmask_b32_e32 v21, v240, v21, vcc
	v_cmp_le_u32_e32 vcc, v99, v92
	v_add_u32_e32 v99, 0x4cf, v93
	v_max3_f32 v98, v98, v20, v21
	v_cndmask_b32_e32 v22, v240, v22, vcc
	v_cmp_le_u32_e32 vcc, v99, v92
	v_or_b32_e32 v99, 0x51f, v93
	s_nop 0
	v_cndmask_b32_e32 v23, v240, v23, vcc
	v_cmp_le_u32_e32 vcc, v99, v92
	v_or_b32_e32 v99, 0x52f, v93
	v_max3_f32 v98, v98, v22, v23
	v_cndmask_b32_e32 v24, v240, v24, vcc
	v_cmp_le_u32_e32 vcc, v99, v92
	v_or_b32_e32 v99, 0x53f, v93
	s_nop 0
	v_cndmask_b32_e32 v25, v240, v25, vcc
	v_cmp_le_u32_e32 vcc, v99, v92
	v_add_u32_e32 v99, 0x54f, v93
	v_max3_f32 v98, v98, v24, v25
	v_cndmask_b32_e32 v26, v240, v26, vcc
	v_cmp_le_u32_e32 vcc, v99, v92
	v_or_b32_e32 v99, 0x59f, v93
	s_nop 0
	v_cndmask_b32_e32 v27, v240, v27, vcc
	v_cmp_le_u32_e32 vcc, v99, v92
	v_or_b32_e32 v99, 0x5af, v93
	v_max3_f32 v98, v98, v26, v27
	v_cndmask_b32_e32 v28, v240, v28, vcc
	v_cmp_le_u32_e32 vcc, v99, v92
	v_or_b32_e32 v99, 0x5bf, v93
	s_nop 0
	v_cndmask_b32_e32 v29, v240, v29, vcc
	v_cmp_le_u32_e32 vcc, v99, v92
	v_add_u32_e32 v99, 0x5cf, v93
	v_max3_f32 v98, v98, v28, v29
	v_cndmask_b32_e32 v30, v240, v30, vcc
	v_cmp_le_u32_e32 vcc, v99, v92
	v_or_b32_e32 v99, 0x61f, v93
	s_nop 0
	v_cndmask_b32_e32 v31, v240, v31, vcc
	v_cmp_le_u32_e32 vcc, v99, v92
	v_max3_f32 v98, v98, v30, v31
	s_nop 0
	v_cndmask_b32_e32 v113, v240, v0, vcc
	v_or_b32_e32 v0, 0x62f, v93
	v_cmp_le_u32_e32 vcc, v0, v92
	s_nop 1
	v_cndmask_b32_e32 v116, v240, v1, vcc
	v_or_b32_e32 v1, 0x63f, v93
	v_cmp_le_u32_e32 vcc, v1, v92
	v_add_u32_e32 v1, 0x64f, v93
	v_max3_f32 v0, v98, v113, v116
	v_cndmask_b32_e32 v117, v240, v2, vcc
	v_cmp_le_u32_e32 vcc, v1, v92
	v_or_b32_e32 v1, 0x69f, v93
	v_and_b32_e32 v2, 64, v238
	v_cndmask_b32_e32 v130, v240, v3, vcc
	v_cmp_le_u32_e32 vcc, v1, v92
	v_or_b32_e32 v1, 0x6af, v93
	v_max3_f32 v0, v0, v117, v130
	v_cndmask_b32_e32 v131, v240, v4, vcc
	v_cmp_le_u32_e32 vcc, v1, v92
	v_or_b32_e32 v1, 0x6bf, v93
	v_add_u32_e32 v144, 64, v2
	v_cndmask_b32_e32 v145, v240, v5, vcc
	v_cmp_le_u32_e32 vcc, v1, v92
	v_add_u32_e32 v1, 0x6cf, v93
	v_max3_f32 v0, v0, v131, v145
	v_cndmask_b32_e32 v147, v240, v6, vcc
	v_cmp_le_u32_e32 vcc, v1, v92
	v_or_b32_e32 v1, 0x71f, v93
	s_nop 0
	v_cndmask_b32_e32 v148, v240, v7, vcc
	v_cmp_le_u32_e32 vcc, v1, v92
	v_or_b32_e32 v1, 0x72f, v93
	v_max3_f32 v0, v0, v147, v148
	v_cndmask_b32_e32 v149, v240, v8, vcc
	v_cmp_le_u32_e32 vcc, v1, v92
	v_or_b32_e32 v1, 0x73f, v93
	s_nop 0
	v_cndmask_b32_e32 v150, v240, v9, vcc
	v_cmp_le_u32_e32 vcc, v1, v92
	v_add_u32_e32 v1, 0x74f, v93
	v_max3_f32 v0, v0, v149, v150
	v_cndmask_b32_e32 v10, v240, v10, vcc
	v_cmp_le_u32_e32 vcc, v1, v92
	v_or_b32_e32 v1, 0x79f, v93
	s_nop 0
	v_cndmask_b32_e32 v11, v240, v11, vcc
	v_cmp_le_u32_e32 vcc, v1, v92
	v_or_b32_e32 v1, 0x7af, v93
	v_max3_f32 v0, v0, v10, v11
	v_cndmask_b32_e32 v12, v240, v12, vcc
	v_cmp_le_u32_e32 vcc, v1, v92
	v_or_b32_e32 v1, 0x7bf, v93
	s_nop 0
	v_cndmask_b32_e32 v13, v240, v13, vcc
	v_cmp_le_u32_e32 vcc, v1, v92
	v_add_u32_e32 v1, 0x7cf, v93
	v_max3_f32 v0, v0, v12, v13
	v_cndmask_b32_e32 v14, v240, v14, vcc
	v_cmp_le_u32_e32 vcc, v1, v92
	v_xor_b32_e32 v1, 32, v238
	s_nop 0
	v_cndmask_b32_e32 v15, v240, v15, vcc
	v_cmp_lt_i32_e32 vcc, v1, v144
	v_max3_f32 v0, v0, v14, v15
	s_nop 0
	v_cndmask_b32_e32 v1, v238, v1, vcc
	v_lshlrev_b32_e32 v134, 2, v1
	ds_bpermute_b32 v1, v134, v0
	s_waitcnt lgkmcnt(0)
; DI void nsa_item(KA a, LAS unsigned char* lds, const int it) {
;     ...
;         mx = fmaxf(mx, __shfl_xor(mx, 32)); const float mref = (mx == -INFINITY) ? 0.f : mx; float ls = 0.f;
; #pragma unroll
;         for (int k4 = 0; k4 < 4; ++k4)
; #pragma unroll
;             for (int i = 0; i < 16; ++i) { const float p = __builtin_amdgcn_exp2f(st[k4][i] - mref); st[k4][i] = p; ls += p; }
;         ls += __shfl_xor(ls, 32); const float inv = ls > 0.f ? 1.f / ls : 0.f;
	v_max_f32_e32 v1, v1, v1
	v_max_f32_e32 v0, v0, v1
	v_cmp_neq_f32_e32 vcc, s0, v0
	s_nop 1
	v_cndmask_b32_e32 v151, 0, v0, vcc
	v_sub_f32_e32 v0, v48, v151
	v_exp_f32_e32 v0, v0
	v_sub_f32_e32 v1, v49, v151
	v_exp_f32_e32 v1, v1
	v_sub_f32_e32 v2, v50, v151
	v_exp_f32_e32 v2, v2
	v_sub_f32_e32 v3, v51, v151
	v_exp_f32_e32 v3, v3
	v_add_f32_e32 v4, 0, v0
	v_add_f32_e32 v4, v1, v4
	v_add_f32_e32 v4, v2, v4
	v_add_f32_e32 v8, v3, v4
	v_sub_f32_e32 v4, v52, v151
	v_exp_f32_e32 v4, v4
	v_sub_f32_e32 v5, v53, v151
	v_exp_f32_e32 v5, v5
	v_sub_f32_e32 v6, v54, v151
	v_exp_f32_e32 v6, v6
	v_sub_f32_e32 v7, v55, v151
	v_exp_f32_e32 v7, v7
	v_sub_f32_e32 v9, v56, v151
	v_add_f32_e32 v8, v4, v8
	v_exp_f32_e32 v126, v9
	v_sub_f32_e32 v9, v57, v151
	v_add_f32_e32 v8, v5, v8
	v_exp_f32_e32 v127, v9
	v_sub_f32_e32 v9, v58, v151
	v_add_f32_e32 v8, v6, v8
	v_exp_f32_e32 v98, v9
	v_sub_f32_e32 v9, v59, v151
	v_add_f32_e32 v8, v7, v8
	v_exp_f32_e32 v99, v9
	v_add_f32_e32 v8, v126, v8
	v_add_f32_e32 v8, v127, v8
	v_add_f32_e32 v8, v98, v8
	v_add_f32_e32 v48, v99, v8
	v_sub_f32_e32 v8, v60, v151
	v_exp_f32_e32 v122, v8
	v_sub_f32_e32 v8, v61, v151
	v_exp_f32_e32 v123, v8
	v_sub_f32_e32 v8, v62, v151
	v_exp_f32_e32 v8, v8
	v_sub_f32_e32 v9, v63, v151
	v_exp_f32_e32 v9, v9
	v_sub_f32_e32 v32, v32, v151
	v_add_f32_e32 v48, v122, v48
	v_exp_f32_e32 v106, v32
	v_sub_f32_e32 v32, v33, v151
	v_add_f32_e32 v48, v123, v48
	v_exp_f32_e32 v107, v32
	v_sub_f32_e32 v32, v34, v151
	v_add_f32_e32 v48, v8, v48
	v_exp_f32_e32 v114, v32
	v_sub_f32_e32 v32, v35, v151
	v_add_f32_e32 v48, v9, v48
	v_exp_f32_e32 v115, v32
	v_sub_f32_e32 v33, v36, v151
	v_add_f32_e32 v32, v106, v48
	v_exp_f32_e32 v120, v33
	v_sub_f32_e32 v33, v37, v151
	v_add_f32_e32 v32, v107, v32
	v_exp_f32_e32 v121, v33
	v_sub_f32_e32 v33, v38, v151
	v_add_f32_e32 v32, v114, v32
	v_exp_f32_e32 v128, v33
	v_sub_f32_e32 v33, v39, v151
	v_add_f32_e32 v32, v115, v32
	v_exp_f32_e32 v129, v33
	v_sub_f32_e32 v33, v40, v151
	v_add_f32_e32 v32, v120, v32
	v_exp_f32_e32 v104, v33
	v_sub_f32_e32 v33, v41, v151
	v_add_f32_e32 v32, v121, v32
	v_exp_f32_e32 v105, v33
	v_sub_f32_e32 v33, v42, v151
	v_add_f32_e32 v32, v128, v32
	v_exp_f32_e32 v110, v33
	v_sub_f32_e32 v33, v43, v151
	v_add_f32_e32 v32, v129, v32
	v_exp_f32_e32 v111, v33
	v_sub_f32_e32 v33, v44, v151
	v_add_f32_e32 v32, v104, v32
	v_exp_f32_e32 v118, v33
	v_sub_f32_e32 v33, v45, v151
	v_add_f32_e32 v32, v105, v32
	v_exp_f32_e32 v119, v33
	v_sub_f32_e32 v33, v46, v151
	v_add_f32_e32 v32, v110, v32
	v_exp_f32_e32 v124, v33
	v_sub_f32_e32 v33, v47, v151
	v_add_f32_e32 v32, v111, v32
	v_exp_f32_e32 v125, v33
	v_sub_f32_e32 v16, v16, v151
	v_add_f32_e32 v32, v118, v32
	v_exp_f32_e32 v52, v16
	v_sub_f32_e32 v16, v17, v151
	v_add_f32_e32 v32, v119, v32
	v_exp_f32_e32 v53, v16
	v_sub_f32_e32 v16, v18, v151
	v_add_f32_e32 v32, v124, v32
	v_exp_f32_e32 v60, v16
	v_sub_f32_e32 v16, v19, v151
	v_add_f32_e32 v32, v125, v32
	v_exp_f32_e32 v61, v16
	v_sub_f32_e32 v17, v20, v151
	v_add_f32_e32 v16, v52, v32
	v_exp_f32_e32 v100, v17
	v_sub_f32_e32 v17, v21, v151
	v_add_f32_e32 v16, v53, v16
	v_exp_f32_e32 v101, v17
	v_sub_f32_e32 v17, v22, v151
	v_add_f32_e32 v16, v60, v16
	v_exp_f32_e32 v108, v17
	v_sub_f32_e32 v17, v23, v151
	v_add_f32_e32 v16, v61, v16
	v_exp_f32_e32 v109, v17
	v_sub_f32_e32 v17, v24, v151
	v_add_f32_e32 v16, v100, v16
	v_exp_f32_e32 v48, v17
	v_sub_f32_e32 v17, v25, v151
	v_add_f32_e32 v16, v101, v16
	v_exp_f32_e32 v49, v17
	v_sub_f32_e32 v17, v26, v151
	v_add_f32_e32 v16, v108, v16
	v_exp_f32_e32 v56, v17
	v_sub_f32_e32 v17, v27, v151
	v_add_f32_e32 v16, v109, v16
	v_exp_f32_e32 v57, v17
	v_sub_f32_e32 v17, v28, v151
	v_add_f32_e32 v16, v48, v16
	v_exp_f32_e32 v92, v17
	v_sub_f32_e32 v17, v29, v151
	v_add_f32_e32 v16, v49, v16
	v_exp_f32_e32 v93, v17
	v_sub_f32_e32 v17, v30, v151
	v_add_f32_e32 v16, v56, v16
	v_exp_f32_e32 v102, v17
	v_sub_f32_e32 v17, v31, v151
	v_add_f32_e32 v16, v57, v16
	v_exp_f32_e32 v103, v17
	v_sub_f32_e32 v17, v113, v151
	v_add_f32_e32 v16, v92, v16
	v_exp_f32_e32 v34, v17
	v_sub_f32_e32 v17, v116, v151
	v_add_f32_e32 v16, v93, v16
	v_exp_f32_e32 v35, v17
	v_sub_f32_e32 v17, v117, v151
	v_add_f32_e32 v16, v102, v16
	v_exp_f32_e32 v38, v17
	v_sub_f32_e32 v17, v130, v151
	v_add_f32_e32 v16, v103, v16
	v_exp_f32_e32 v39, v17
	v_sub_f32_e32 v17, v131, v151
	v_add_f32_e32 v16, v34, v16
	v_exp_f32_e32 v42, v17
	v_sub_f32_e32 v17, v145, v151
	v_add_f32_e32 v16, v35, v16
	v_exp_f32_e32 v43, v17
	v_sub_f32_e32 v17, v147, v151
	v_add_f32_e32 v16, v38, v16
	v_exp_f32_e32 v54, v17
	v_sub_f32_e32 v17, v148, v151
	v_add_f32_e32 v16, v39, v16
	v_exp_f32_e32 v55, v17
	v_sub_f32_e32 v17, v149, v151
	v_add_f32_e32 v16, v42, v16
	v_exp_f32_e32 v32, v17
	v_sub_f32_e32 v17, v150, v151
	v_add_f32_e32 v16, v43, v16
	v_exp_f32_e32 v33, v17
	v_sub_f32_e32 v10, v10, v151
	v_add_f32_e32 v16, v54, v16
	v_exp_f32_e32 v36, v10
	v_sub_f32_e32 v10, v11, v151
	v_add_f32_e32 v16, v55, v16
	v_exp_f32_e32 v37, v10
	v_sub_f32_e32 v11, v12, v151
	v_add_f32_e32 v10, v32, v16
	v_exp_f32_e32 v40, v11
	v_sub_f32_e32 v11, v13, v151
	v_add_f32_e32 v10, v33, v10
	v_exp_f32_e32 v41, v11
	v_sub_f32_e32 v11, v14, v151
	v_add_f32_e32 v10, v36, v10
	v_exp_f32_e32 v44, v11
	v_sub_f32_e32 v11, v15, v151
	v_add_f32_e32 v10, v37, v10
	v_exp_f32_e32 v45, v11
	v_add_f32_e32 v10, v40, v10
	v_add_f32_e32 v10, v41, v10
	v_add_f32_e32 v10, v44, v10
	v_add_f32_e32 v10, v45, v10
	ds_bpermute_b32 v11, v134, v10
	v_mad_u32_u24 v59, v89, s4, v112
	s_waitcnt lgkmcnt(0)
; DI f32x16 mma32(bf16x8 a, bf16x8 b, f32x16 c) { return __builtin_amdgcn_mfma_f32_32x32x16_bf16(a, b, c, 0, 0, 0); }
; DI bf16x8 packp(const f32x16& x, const int h8) { v4u p; p.x = pk2(x[h8 + 0], x[h8 + 1]); p.y = pk2(x[h8 + 2], x[h8 + 3]); p.z = pk2(x[h8 + 4], x[h8 + 5]); p.w = pk2(x[h8 + 6], x[h8 + 7]); return __builtin_bit_cast(bf16x8, p); }
; DI void nsa_item(KA a, LAS unsigned char* lds, const int it) {
;     ...
;         ls += __shfl_xor(ls, 32); const float inv = ls > 0.f ? 1.f / ls : 0.f;
; #pragma unroll
;         for (int k4 = 0; k4 < 4; ++k4) st[k4] = st[k4] * inv;
;         f32x16 ot[2] = {ZERO16, ZERO16};
; #pragma unroll
;         for (int sp = 0; sp < 8; ++sp) { const bf16x8 pf = packp(st[sp >> 1], 8 * (sp & 1));
; #pragma unroll
;             for (int dh = 0; dh < 2; ++dh) ot[dh] = mma32(vfrag(VT, 32 * dh + r, sp, hf), pf, ot[dh]); }
;         of[0] = ot[0] * g0; of[1] = ot[1] * g0;
;         if (qb >= 16) {
	v_add_f32_e32 v10, v10, v11
	v_div_scale_f32 v11, s[0:1], v10, v10, 1.0
	v_rcp_f32_e32 v12, v11
	s_mov_b64 s[0:1], -1
	v_fma_f32 v13, -v11, v12, 1.0
	v_fmac_f32_e32 v12, v13, v12
	v_div_scale_f32 v13, vcc, 1.0, v10, 1.0
	v_mul_f32_e32 v14, v13, v12
	v_fma_f32 v15, -v11, v14, v13
	v_fmac_f32_e32 v14, v15, v12
	v_fma_f32 v11, -v11, v14, v13
	v_div_fmas_f32 v11, v11, v12, v14
	v_div_fixup_f32 v11, v11, v10, 1.0
	v_cmp_lt_f32_e32 vcc, 0, v10
	s_nop 1
	v_cndmask_b32_e32 v58, 0, v11, vcc
	ds_read_b128 v[10:13], v59 offset:18432
	v_pk_mul_f32 v[46:47], v[6:7], v[58:59] op_sel_hi:[1,0]
	v_pk_mul_f32 v[112:113], v[4:5], v[58:59] op_sel_hi:[1,0]
	v_pk_mul_f32 v[50:51], v[2:3], v[58:59] op_sel_hi:[1,0]
	v_pk_mul_f32 v[116:117], v[0:1], v[58:59] op_sel_hi:[1,0]
	v_cvt_pk_bf16_f32 v1, v50, v51
	v_cvt_pk_bf16_f32 v0, v116, v117
	v_cvt_pk_bf16_f32 v2, v112, v113
	v_cvt_pk_bf16_f32 v3, v46, v47
	ds_read_b128 v[4:7], v59 offset:27136
	ds_read_b128 v[148:151], v59 offset:18464
	s_waitcnt lgkmcnt(2)
	v_mfma_f32_32x32x16_bf16 v[16:31], v[10:13], v[0:3], 0
	v_mul_f32_e64 v62, v8, v58
	v_mul_f32_e64 v63, v9, v58
	v_mul_f32_e64 v122, v122, v58
	v_mul_f32_e64 v123, v123, v58
	v_mul_f32_e64 v98, v98, v58
	v_mul_f32_e64 v99, v99, v58
	v_pk_mul_f32 v[126:127], v[126:127], v[58:59] op_sel_hi:[1,0]
	v_cvt_pk_bf16_f32 v153, v98, v99
	v_cvt_pk_bf16_f32 v152, v126, v127
	v_cvt_pk_bf16_f32 v154, v122, v123
	v_cvt_pk_bf16_f32 v155, v62, v63
	s_waitcnt lgkmcnt(1)
	v_mfma_f32_32x32x16_bf16 v[0:15], v[4:7], v[0:3], 0
	ds_read_b128 v[156:159], v59 offset:18496
	v_mul_f32_e64 v128, v128, v58
	v_mul_f32_e64 v129, v129, v58
	v_mul_f32_e64 v120, v120, v58
	v_mul_f32_e64 v121, v121, v58
	v_pk_mul_f32 v[114:115], v[114:115], v[58:59] op_sel_hi:[1,0]
	v_pk_mul_f32 v[130:131], v[106:107], v[58:59] op_sel_hi:[1,0]
	v_pk_mul_f32 v[106:107], v[124:125], v[58:59] op_sel_hi:[1,0]
	v_pk_mul_f32 v[118:119], v[118:119], v[58:59] op_sel_hi:[1,0]
	s_waitcnt lgkmcnt(1)
	v_mfma_f32_32x32x16_bf16 v[16:31], v[148:151], v[152:155], v[16:31]
	ds_read_b128 v[148:151], v59 offset:27168
	v_mul_f32_e64 v110, v110, v58
	v_mul_f32_e64 v111, v111, v58
	v_mul_f32_e64 v104, v104, v58
	v_mul_f32_e64 v105, v105, v58
	v_pk_mul_f32 v[108:109], v[108:109], v[58:59] op_sel_hi:[1,0]
	v_pk_mul_f32 v[100:101], v[100:101], v[58:59] op_sel_hi:[1,0]
	v_pk_mul_f32 v[60:61], v[60:61], v[58:59] op_sel_hi:[1,0]
	v_pk_mul_f32 v[124:125], v[52:53], v[58:59] op_sel_hi:[1,0]
	s_waitcnt lgkmcnt(0)
	v_mfma_f32_32x32x16_bf16 v[0:15], v[148:151], v[152:155], v[0:15]
	v_cvt_pk_bf16_f32 v148, v130, v131
	v_cvt_pk_bf16_f32 v149, v114, v115
	v_cvt_pk_bf16_f32 v150, v120, v121
	v_cvt_pk_bf16_f32 v151, v128, v129
	v_mul_f32_e64 v52, v102, v58
	v_mul_f32_e64 v53, v103, v58
	v_pk_mul_f32 v[102:103], v[92:93], v[58:59] op_sel_hi:[1,0]
	v_pk_mul_f32 v[56:57], v[56:57], v[58:59] op_sel_hi:[1,0]
	v_mfma_f32_32x32x16_bf16 v[16:31], v[156:159], v[148:151], v[16:31]
	ds_read_b128 v[152:155], v59 offset:27200
	ds_read_b128 v[156:159], v59 offset:18528
	v_mul_f32_e64 v48, v48, v58
	v_mul_f32_e64 v49, v49, v58
	v_mul_f32_e64 v54, v54, v58
	v_mul_f32_e64 v55, v55, v58
	v_pk_mul_f32 v[42:43], v[42:43], v[58:59] op_sel_hi:[1,0]
	v_pk_mul_f32 v[38:39], v[38:39], v[58:59] op_sel_hi:[1,0]
	v_pk_mul_f32 v[34:35], v[34:35], v[58:59] op_sel_hi:[1,0]
	v_pk_mul_f32 v[44:45], v[44:45], v[58:59] op_sel_hi:[1,0]
	s_waitcnt lgkmcnt(1)
	v_mfma_f32_32x32x16_bf16 v[0:15], v[152:155], v[148:151], v[0:15]
	ds_read_b128 v[152:155], v59 offset:27232
	v_cvt_pk_bf16_f32 v148, v104, v105
	v_cvt_pk_bf16_f32 v149, v110, v111
	v_cvt_pk_bf16_f32 v150, v118, v119
	v_cvt_pk_bf16_f32 v151, v106, v107
	v_pk_mul_f32 v[40:41], v[40:41], v[58:59] op_sel_hi:[1,0]
	v_pk_mul_f32 v[36:37], v[36:37], v[58:59] op_sel_hi:[1,0]
	s_waitcnt lgkmcnt(1)
	v_mfma_f32_32x32x16_bf16 v[16:31], v[156:159], v[148:151], v[16:31]
	ds_read_b128 v[156:159], v59 offset:18560
	v_mul_f32_e64 v32, v32, v58
	v_mul_f32_e64 v33, v33, v58
	v_lshlrev_b32_e32 v58, 2, v141
	s_waitcnt lgkmcnt(1)
	v_mfma_f32_32x32x16_bf16 v[0:15], v[152:155], v[148:151], v[0:15]
	v_cvt_pk_bf16_f32 v148, v124, v125
	v_cvt_pk_bf16_f32 v149, v60, v61
	v_cvt_pk_bf16_f32 v150, v100, v101
	v_cvt_pk_bf16_f32 v151, v108, v109
	s_waitcnt lgkmcnt(0)
	s_nop 0
	v_mfma_f32_32x32x16_bf16 v[16:31], v[156:159], v[148:151], v[16:31]
	ds_read_b128 v[152:155], v59 offset:27264
	ds_read_b128 v[156:159], v59 offset:18592
	s_waitcnt lgkmcnt(1)
	v_mfma_f32_32x32x16_bf16 v[0:15], v[152:155], v[148:151], v[0:15]
	ds_read_b128 v[152:155], v59 offset:27296
	v_cvt_pk_bf16_f32 v148, v48, v49
	v_cvt_pk_bf16_f32 v149, v56, v57
	v_cvt_pk_bf16_f32 v150, v102, v103
	v_cvt_pk_bf16_f32 v151, v52, v53
	s_waitcnt lgkmcnt(1)
	s_nop 0
	v_mfma_f32_32x32x16_bf16 v[16:31], v[156:159], v[148:151], v[16:31]
	ds_read_b128 v[156:159], v59 offset:18624
	s_waitcnt lgkmcnt(1)
	v_mfma_f32_32x32x16_bf16 v[0:15], v[152:155], v[148:151], v[0:15]
	v_cvt_pk_bf16_f32 v148, v34, v35
	v_cvt_pk_bf16_f32 v149, v38, v39
	v_cvt_pk_bf16_f32 v150, v42, v43
	v_cvt_pk_bf16_f32 v151, v54, v55
	s_waitcnt lgkmcnt(0)
	s_nop 0
	v_mfma_f32_32x32x16_bf16 v[16:31], v[156:159], v[148:151], v[16:31]
	ds_read_b128 v[152:155], v59 offset:27328
	ds_read_b128 v[156:159], v59 offset:18656
	s_waitcnt lgkmcnt(1)
	v_mfma_f32_32x32x16_bf16 v[0:15], v[152:155], v[148:151], v[0:15]
	ds_read_b128 v[152:155], v59 offset:27360
	v_cvt_pk_bf16_f32 v148, v32, v33
	v_cvt_pk_bf16_f32 v149, v36, v37
	v_cvt_pk_bf16_f32 v150, v40, v41
	v_cvt_pk_bf16_f32 v151, v44, v45
	s_waitcnt lgkmcnt(1)
	s_nop 0
	v_mfma_f32_32x32x16_bf16 v[16:31], v[156:159], v[148:151], v[16:31]
	s_waitcnt lgkmcnt(0)
	v_mfma_f32_32x32x16_bf16 v[0:15], v[152:155], v[148:151], v[0:15]
	s_cbranch_scc0 .LBB0_610
	v_lshlrev_b32_e32 v145, 2, v141
	s_mov_b64 s[0:1], 0
